# window-item loops: same 4-slot ring with the DMA issued before the barrier; bias-table build writes wait only for their own read (counted lgkmcnt) instead of draining LDS before every write
# baseline (speedup 1.0000x reference)
; #define TIDX get_tid_()
; DI void nsa_win_item(const Params& p, int b, int head, int qb, const unsigned char* blut, const float* tbl) {
;   const int lane = TIDX & 63, r = lane & 31, h = lane >> 5;
;   const int g = head / 3, bg = b * 2 + g;
;   const int t = qb * 32 + r;
;   const float* tblh = tbl + head * 32;
;   bf16x8 qf[4];
;   load_q(qf, (const bf16_t*)(p.ws + OFF_QN) + (size_t)(b * 4096 + t) * 384 + head * 64 + 8 * h);
;   const float g2 = ((const float*)(p.ws + OFF_GATES))[(size_t)(b * 4096 + t) * 18 + head * 3 + 2];
;   f32x16 y0, y1;
; #pragma unroll
;   for (int i = 0; i < 16; ++i) { y0[i] = 0.f; y1[i] = 0.f; }
;   {
;     const bf16_t* K = (const bf16_t*)(p.ws + OFF_KWIN) + (size_t)bg * 4096 * 64;
;     const bf16_t* Vt = (const bf16_t*)(p.ws + OFF_VWINT) + (size_t)bg * 64 * 4096;
;     AttnSt st; attn_init(st);
;     const int k0 = qb >= 16 ? qb - 16 : 0;
;     ...
;     const int item = wave_fetch(ctr);
;     if (item >= 2048 + 32 * 48) break;
;     if (item < 2048) nsa_cmp_item(p, item, blut, tbl, (float*)(lds + 8192) + (TIDX >> 6) * (32 * 65));
;     else { const int it2 = item - 2048, qb = 31 - it2 / 48, sub = it2 % 48; nsa_win_item(p, sub / 6, sub % 6, qb, blut, tbl); }
.Lf6_done:
	v_mov_b32_e32 v2, s10
	s_movk_i32 s8, 0xe00
	s_waitcnt lgkmcnt(0)
	v_cmp_gt_i32_e32 vcc, s8, v2
	s_mov_b64 s[8:9], -1
	s_and_saveexec_b64 s[68:69], vcc
	s_cbranch_execz .LBB0_143
	s_movk_i32 s8, 0x7ff
	v_cmp_lt_i32_e32 vcc, s8, v2
	s_and_saveexec_b64 s[8:9], vcc
	s_xor_b64 s[8:9], exec, s[8:9]
	s_cbranch_execz .LBB0_158
	v_add_u16_e32 v0, 0xf800, v2
	v_mul_u32_u24_e32 v1, 0xaaab, v0
	v_lshrrev_b32_e32 v32, 21, v1
	v_mul_lo_u16_e32 v1, 48, v32
	v_sub_u16_e32 v0, v0, v1
	s_movk_i32 s10, 0xab
	v_mul_lo_u16_sdwa v1, v0, s10 dst_sel:DWORD dst_unused:UNUSED_PAD src0_sel:BYTE_0 src1_sel:DWORD
	v_lshrrev_b16_e32 v4, 10, v1
	v_mul_lo_u16_e32 v1, 6, v4
	v_sub_u16_e32 v33, v0, v1
	v_mov_b32_e32 v0, v129
	v_sub_u32_sdwa v138, v200, v32 dst_sel:DWORD dst_unused:UNUSED_PAD src0_sel:DWORD src1_sel:WORD_0
	v_readlane_b32 s10, v253, 13
	v_and_b32_e32 v34, 31, v0
	v_bfe_u32 v35, v0, 5, 1
	v_lshlrev_b32_e32 v0, 5, v138
	v_lshlrev_b32_e32 v1, 12, v4
	v_readlane_b32 s11, v253, 14
	v_or3_b32 v113, v34, v0, v1
	v_lshlrev_b32_sdwa v130, v202, v33 dst_sel:DWORD dst_unused:UNUSED_PAD src0_sel:DWORD src1_sel:BYTE_0
	v_mov_b64_e32 v[0:1], s[10:11]
	s_movk_i32 s10, 0x300
	v_mad_u64_u32 v[0:1], s[10:11], v113, s10, v[0:1]
	v_lshl_add_u64 v[0:1], v[0:1], 0, v[130:131]
	v_lshlrev_b32_e32 v2, 4, v35
	v_mov_b32_e32 v3, v131
	v_cmp_gt_u16_sdwa vcc, v33, v204 src0_sel:BYTE_0 src1_sel:DWORD
	v_lshl_add_u64 v[8:9], v[0:1], 0, v[2:3]
	v_readlane_b32 s10, v253, 31
	v_cndmask_b32_e32 v0, 0, v205, vcc
	v_add_u32_e32 v139, 0, v130
	v_lshl_or_b32 v130, v4, 20, v0
	v_readlane_b32 s11, v253, 32
	v_sub_u32_sdwa v36, v206, v32 clamp dst_sel:DWORD dst_unused:UNUSED_PAD src0_sel:DWORD src1_sel:WORD_0
	v_lshlrev_b32_e32 v2, 3, v34
	v_lshl_add_u64 v[24:25], s[10:11], 0, v[130:131]
	v_readlane_b32 s10, v253, 33
	v_readlane_b32 s11, v253, 34
	v_lshl_or_b32 v28, v35, 8, v2
	v_lshlrev_b32_e32 v30, 1, v28
	v_lshl_add_u64 v[26:27], s[10:11], 0, v[130:131]
	v_lshlrev_b32_e32 v130, 12, v36
	v_lshl_add_u64 v[0:1], v[24:25], 0, v[130:131]
	v_mov_b32_e32 v31, v131
	v_lshl_add_u64 v[10:11], v[0:1], 0, v[30:31]
	global_load_dwordx4 v[0:3], v[10:11], off
	global_load_dwordx4 v[64:67], v[8:9], off
	v_readlane_b32 s10, v253, 29
	v_readlane_b32 s11, v253, 30
	v_mul_u32_u24_sdwa v6, v33, v203 dst_sel:DWORD dst_unused:UNUSED_PAD src0_sel:BYTE_0 src1_sel:DWORD
	v_lshlrev_b32_e32 v14, 2, v6
	v_mov_b64_e32 v[4:5], s[10:11]
	s_movk_i32 s10, 0x48
	v_mad_u64_u32 v[12:13], s[10:11], v113, s10, v[4:5]
	global_load_dwordx4 v[4:7], v[10:11], off offset:1024
	v_mov_b32_e32 v15, v131
	v_lshl_add_u64 v[12:13], v[12:13], 0, v[14:15]
	global_load_dword v140, v[12:13], off
	global_load_dwordx4 v[68:71], v[8:9], off offset:32
	global_load_dwordx4 v[72:75], v[8:9], off offset:64
	global_load_dwordx4 v[76:79], v[8:9], off offset:96
	global_load_dwordx4 v[16:19], v[10:11], off offset:2048
	global_load_dwordx4 v[20:23], v[10:11], off offset:3072
	v_add_u32_e32 v8, 1, v36
	v_cmp_lt_u32_e32 vcc, v36, v138
	v_mov_b32_e32 v9, v131
	v_mov_b32_e32 v29, v131
	v_cndmask_b32_e32 v8, v138, v8, vcc
	v_lshlrev_b32_e32 v8, 12, v8
	v_lshl_add_u64 v[8:9], v[24:25], 0, v[8:9]
	v_lshl_add_u64 v[10:11], v[26:27], 0, v[130:131]
	v_lshl_add_u64 v[8:9], v[8:9], 0, v[30:31]
	v_lshl_add_u64 v[10:11], v[10:11], 0, v[28:29]
	global_load_dwordx4 v[88:91], v[8:9], off offset:2048
	global_load_dwordx4 v[80:83], v[8:9], off offset:1024
	global_load_dwordx4 v[92:95], v[8:9], off
	global_load_dwordx2 v[86:87], v[10:11], off offset:3584
	global_load_dwordx2 v[84:85], v[10:11], off offset:3072
	global_load_dwordx2 v[102:103], v[10:11], off offset:2560
	global_load_dwordx2 v[100:101], v[10:11], off offset:2048
	global_load_dwordx2 v[106:107], v[10:11], off offset:1536
	global_load_dwordx2 v[104:105], v[10:11], off offset:1024
	global_load_dwordx2 v[110:111], v[10:11], off offset:512
	global_load_dwordx4 v[96:99], v[8:9], off offset:3072
	global_load_dwordx2 v[108:109], v[10:11], off
	s_mov_b32 s53, s52
	v_lshlrev_b32_e32 v141, 2, v35
	s_mov_b32 s54, s52
	s_mov_b32 s55, s52
	s_mov_b32 s56, s52
	s_mov_b32 s57, s52
	s_mov_b32 s58, s52
	s_mov_b32 s59, s52
	s_mov_b32 s60, s52
	s_mov_b32 s61, s52
	s_mov_b32 s62, s52
	s_mov_b32 s63, s52
	s_mov_b32 s64, s52
	s_mov_b32 s65, s52
	s_mov_b32 s66, s52
	s_mov_b32 s67, s52
	v_lshl_add_u64 v[114:115], v[26:27], 0, v[28:29]
	v_lshl_add_u64 v[116:117], v[24:25], 0, v[30:31]
	v_lshlrev_b32_sdwa v112, v201, v33 dst_sel:DWORD dst_unused:UNUSED_PAD src0_sel:DWORD src1_sel:BYTE_0
	v_mov_b32_e32 v145, 0
	v_mov_b32_e32 v146, 0xff800000
	s_mov_b64 s[10:11], 0
	s_waitcnt vmcnt(19)
	v_mfma_f32_32x32x16_bf16 v[48:63], v[0:3], v[64:67], 0
	s_waitcnt vmcnt(16)
	v_mfma_f32_32x32x16_bf16 v[48:63], v[4:7], v[68:71], v[48:63]
	v_mov_b64_e32 v[0:1], s[52:53]
	v_mov_b64_e32 v[14:15], s[66:67]
	v_mov_b64_e32 v[2:3], s[54:55]
	v_mov_b64_e32 v[4:5], s[56:57]
	v_mov_b64_e32 v[6:7], s[58:59]
	v_mov_b64_e32 v[8:9], s[60:61]
	v_mov_b64_e32 v[10:11], s[62:63]
	s_waitcnt vmcnt(13)
	v_mfma_f32_32x32x16_bf16 v[48:63], v[16:19], v[72:75], v[48:63]
	v_min_u32_sdwa v16, v32, v206 dst_sel:DWORD dst_unused:UNUSED_PAD src0_sel:WORD_0 src1_sel:DWORD
	v_lshl_or_b32 v17, v16, 5, v34
	v_sub_u32_e32 v17, v17, v141
	v_lshlrev_b32_sdwa v18, v207, v32 dst_sel:DWORD dst_unused:UNUSED_PAD src0_sel:DWORD src1_sel:WORD_0
	v_sub_u32_e32 v17, v17, v18
	v_mov_b64_e32 v[12:13], s[64:65]
	v_add_u32_e32 v142, 0x1e5, v17
	s_waitcnt vmcnt(12)
	v_mfma_f32_32x32x16_bf16 v[48:63], v[20:23], v[76:79], v[48:63]
	v_sub_u32_e32 v143, 17, v16
	v_mov_b64_e32 v[30:31], v[14:15]
	v_mov_b64_e32 v[28:29], v[12:13]
	v_mov_b64_e32 v[26:27], v[10:11]
	v_mov_b64_e32 v[24:25], v[8:9]
	v_mov_b64_e32 v[22:23], v[6:7]
	v_mov_b64_e32 v[20:21], v[4:5]
	v_mov_b64_e32 v[18:19], v[2:3]
	v_mov_b64_e32 v[16:17], v[0:1]
	s_waitcnt vmcnt(0)
	v_readfirstlane_b32 s60, v138
	v_lshrrev_b32_e32 v246, 6, v129
	v_and_b32_e32 v247, 63, v129
	v_lshlrev_b32_e32 v247, 3, v247
	v_readfirstlane_b32 s58, v246
	s_sub_u32 s65, s60, 16
	s_cmp_lt_u32 s60, 16
	s_cselect_b32 s65, 0, s65
	s_mov_b64 s[62:63], -1
	v_mov_b32_e32 v223, 0xff800000
	v_and_b32_e32 v222, 31, v129
	v_bfe_u32 v240, v129, 5, 1
	v_lshlrev_b32_e32 v240, 2, v240
	v_sub_u32_e32 v222, v222, v240
	v_mov_b32_e32 v32, s60
	v_mov_b32_e32 v33, 0x1940
	v_lshl_add_u32 v42, v246, 2, v33
	ds_write_b32 v42, v32
	s_waitcnt lgkmcnt(0)
	s_barrier
; template <class KP, class VP, class ACT, class FILL>
; DI void attn_loop(AttnSt& st, const bf16x8 (&qf)[4], int k0, int k1, size_t vstride, KP kp, VP vp, ACT act, FILL fill) {
;     ...
;   for (int kt = k0; kt <= k1; ++kt) {
;     const int kn = (kt < k1) ? kt + 1 : k1;
;     const int kn2 = (kt + 2 <= k1) ? kt + 2 : k1;
;     {
;       const bf16_t* v0 = vp(kn);
; #pragma unroll
;       for (int j = 0; j < 8; ++j) nxt.v[j] = *(const s16x4*)(v0 + 256 * j);
;     }
;     bf16x8 k2[4];
;     {
;       const bf16_t* krow = kp(kn2);
; #pragma unroll
;       for (int ss = 0; ss < 4; ++ss) k2[ss] = *(const bf16x8*)(krow + 512 * ss);
;     }
; DI void bias16(const unsigned char* blut, const float* tblh, const int (&dist)[16], float (&bv)[16]) {
;   int bk[16];
; #pragma unroll
;   for (int i = 0; i < 16; ++i) { const int d = dist[i] < 0 ? 0 : (dist[i] > 2048 ? 2048 : dist[i]); bk[i] = blut[d]; }
; #pragma unroll
;   for (int i = 0; i < 16; ++i) asm volatile("" : "+v"(bk[i]));
; #pragma unroll
;   for (int i = 0; i < 16; ++i) bv[i] = tblh[bk[i]];
; #pragma unroll
;   for (int i = 0; i < 16; ++i) asm volatile("" : "+v"(bv[i]));
; }
	ds_read_b128 v[34:37], v33
	ds_read_b128 v[38:41], v33 offset:16
	s_waitcnt lgkmcnt(0)
	v_min3_u32 v42, v34, v35, v36
	v_min3_u32 v42, v42, v37, v38
	v_min3_u32 v42, v42, v39, v40
	v_min_u32_e32 v42, v42, v41
	v_max3_u32 v34, v34, v35, v36
	v_max3_u32 v34, v34, v37, v38
	v_max3_u32 v34, v34, v39, v40
	v_max_u32_e32 v34, v34, v41
	s_nop 0
	v_readfirstlane_b32 s59, v34
	v_readfirstlane_b32 s66, v42
	s_sub_u32 s56, s66, 16
	s_cmp_lt_u32 s66, 16
	s_cselect_b32 s56, 0, s56
	s_and_b32 s56, s56, -2
	s_lshr_b32 s23, s56, 1
	s_mov_b32 s64, 0x10000
	s_lshr_b32 s24, s59, 1
	s_min_u32 s24, s23, s24
	s_lshl_b32 s26, s24, 13
	s_lshl_b32 s24, s58, 10
	s_add_u32 s26, s26, s24
	s_mov_b32 s27, 0
	v_lshl_add_u64 v[248:249], v[116:117], 0, s[26:27]
	v_lshl_add_u64 v[250:251], v[114:115], 0, s[26:27]
	v_add_co_u32_e32 v250, vcc, v250, v247
	v_addc_co_u32_e32 v251, vcc, 0, v251, vcc
	s_add_u32 s24, s24, s64
	s_mov_b32 m0, s24
	s_nop 0
	global_load_lds_dwordx4 v[248:249], off
	s_add_u32 s24, s24, 0x2000
	s_mov_b32 m0, s24
	s_nop 0
	global_load_lds_dwordx4 v[250:251], off
	s_lshr_b32 s23, s56, 1
	s_add_u32 s23, s23, 1
	s_mov_b32 s64, 0x14000
	s_lshr_b32 s24, s59, 1
	s_min_u32 s24, s23, s24
	s_lshl_b32 s26, s24, 13
	s_lshl_b32 s24, s58, 10
	s_add_u32 s26, s26, s24
	s_mov_b32 s27, 0
	v_lshl_add_u64 v[248:249], v[116:117], 0, s[26:27]
	v_lshl_add_u64 v[250:251], v[114:115], 0, s[26:27]
	v_add_co_u32_e32 v250, vcc, v250, v247
	v_addc_co_u32_e32 v251, vcc, 0, v251, vcc
	s_add_u32 s24, s24, s64
	s_mov_b32 m0, s24
	s_nop 0
	global_load_lds_dwordx4 v[248:249], off
	s_add_u32 s24, s24, 0x2000
	s_mov_b32 m0, s24
	s_nop 0
	global_load_lds_dwordx4 v[250:251], off
	s_mov_b32 s64, 0x10000
	v_lshrrev_b32_e32 v246, 6, v129
	v_mul_u32_u24_e32 v246, 6912, v246
	v_add_u32_e32 v242, 8192, v246
	v_and_b32_e32 v246, 63, v129
	v_mov_b32_e32 v80, 0
	v_mov_b32_e32 v81, v246
	v_add_u32_e32 v82, 64, v246
	v_add_u32_e32 v83, 128, v246
	v_add_u32_e32 v84, 192, v246
	v_add_u32_e32 v85, 256, v246
	v_add_u32_e32 v86, 320, v246
	v_add_u32_e32 v87, 384, v246
	v_add_u32_e32 v88, 448, v246
	v_add_u32_e32 v89, 512, v246
	ds_read_u8 v80, v80
	ds_read_u8 v81, v81
	ds_read_u8 v82, v82
	ds_read_u8 v83, v83
	ds_read_u8 v84, v84
	ds_read_u8 v85, v85
	ds_read_u8 v86, v86
	ds_read_u8 v87, v87
	ds_read_u8 v88, v88
	ds_read_u8 v89, v89
	s_waitcnt lgkmcnt(9)
	v_lshl_add_u32 v80, v80, 2, v139
	s_waitcnt lgkmcnt(8)
	v_lshl_add_u32 v81, v81, 2, v139
	s_waitcnt lgkmcnt(7)
	v_lshl_add_u32 v82, v82, 2, v139
	s_waitcnt lgkmcnt(6)
	v_lshl_add_u32 v83, v83, 2, v139
	s_waitcnt lgkmcnt(5)
	v_lshl_add_u32 v84, v84, 2, v139
	s_waitcnt lgkmcnt(4)
	v_lshl_add_u32 v85, v85, 2, v139
	s_waitcnt lgkmcnt(3)
	v_lshl_add_u32 v86, v86, 2, v139
	s_waitcnt lgkmcnt(2)
	v_lshl_add_u32 v87, v87, 2, v139
	s_waitcnt lgkmcnt(1)
	v_lshl_add_u32 v88, v88, 2, v139
	s_waitcnt lgkmcnt(0)
	v_lshl_add_u32 v89, v89, 2, v139
	ds_read_b32 v80, v80 offset:4096
	ds_read_b32 v81, v81 offset:4096
	ds_read_b32 v82, v82 offset:4096
	ds_read_b32 v83, v83 offset:4096
	ds_read_b32 v84, v84 offset:4096
	ds_read_b32 v85, v85 offset:4096
	ds_read_b32 v86, v86 offset:4096
	ds_read_b32 v87, v87 offset:4096
	ds_read_b32 v88, v88 offset:4096
	ds_read_b32 v89, v89 offset:4096
	v_lshl_add_u32 v244, v246, 2, v242
	s_waitcnt lgkmcnt(9)
	ds_write_b32 v244, v80 offset:0
	s_waitcnt lgkmcnt(9)
	ds_write_b32 v244, v81 offset:256
	s_waitcnt lgkmcnt(9)
	ds_write_b32 v244, v82 offset:512
	s_waitcnt lgkmcnt(9)
	ds_write_b32 v244, v83 offset:768
	s_waitcnt lgkmcnt(9)
	ds_write_b32 v244, v84 offset:1024
	s_waitcnt lgkmcnt(9)
	ds_write_b32 v244, v85 offset:1280
	s_waitcnt lgkmcnt(9)
	ds_write_b32 v244, v86 offset:1536
	s_waitcnt lgkmcnt(9)
	ds_write_b32 v244, v87 offset:1792
	s_waitcnt lgkmcnt(9)
	ds_write_b32 v244, v88 offset:2048
	s_waitcnt lgkmcnt(9)
	ds_write_b32 v244, v89 offset:2304
	ds_read_b32 v240, v139 offset:4220
	v_add_u32_e32 v242, 148, v242
	v_mov_b32_e32 v243, 0x7f800000
	s_waitcnt lgkmcnt(0)
.Lawin6_loop:
	s_lshr_b32 s23, s56, 1
	s_add_u32 s23, s23, 2
	s_add_u32 s61, s64, 0x8000
	s_sub_u32 s24, s61, 0x10000
	s_cmp_ge_u32 s61, 0x20000
	s_cselect_b32 s61, s24, s61
	s_lshr_b32 s24, s59, 1
	s_min_u32 s24, s23, s24
	s_lshl_b32 s26, s24, 13
	s_lshl_b32 s24, s58, 10
	s_add_u32 s26, s26, s24
	s_mov_b32 s27, 0
	v_lshl_add_u64 v[248:249], v[116:117], 0, s[26:27]
	v_lshl_add_u64 v[250:251], v[114:115], 0, s[26:27]
	v_add_co_u32_e32 v250, vcc, v250, v247
	v_addc_co_u32_e32 v251, vcc, 0, v251, vcc
	s_add_u32 s24, s24, s61
	s_mov_b32 m0, s24
	s_nop 0
	global_load_lds_dwordx4 v[248:249], off
	s_add_u32 s24, s24, 0x2000
	s_mov_b32 m0, s24
	s_nop 0
	global_load_lds_dwordx4 v[250:251], off
	s_waitcnt vmcnt(4)
	s_barrier
	s_cmp_le_u32 s56, s60
	s_cbranch_scc0 .Lawin6_skip
	s_add_u32 s24, s56, 1
	s_cmp_ge_u32 s24, s65
	s_cbranch_scc0 .Lawin6_skip
; #define NEGINF (-__builtin_inff())
; DI int crow(int i, int h) { return (i & 3) + 8 * (i >> 2) + 4 * h; }
; DI void nsa_win_item(const Params& p, int b, int head, int qb, const unsigned char* blut, const float* tbl) {
;     ...
;     attn_loop(st, qf, k0, qb, 32,
;       [&](int kt) { return K + (size_t)kt * 2048 + (h * 32 + r) * 8; },
;       [&](int kt) { return Vt + (size_t)kt * 2048 + (h * 32 + r) * 4; },
;       [&](int kt) { return true; },
;       [&](int kt, const f32x16& s, float (&lg)[16]) {
;         int dist[16]; float bv[16];
; #pragma unroll
;         for (int i = 0; i < 16; ++i) dist[i] = t - (kt * 32 + crow(i, h));
;         bias16(blut, tblh, dist, bv);
; #pragma unroll
;         for (int i = 0; i < 16; ++i) lg[i] = (dist[i] >= 0 && dist[i] < 512) ? s[i] + bv[i] : NEGINF;
;       });
	v_lshl_add_u32 v248, v247, 1, s64
	ds_read_b128 v[80:83], v248 offset:0
	ds_read_b128 v[96:99], v248 offset:4096
	ds_read_b128 v[84:87], v248 offset:1024
	ds_read_b128 v[100:103], v248 offset:5120
	ds_read_b128 v[88:91], v248 offset:2048
	ds_read_b128 v[104:107], v248 offset:6144
	ds_read_b128 v[92:95], v248 offset:3072
	ds_read_b128 v[108:111], v248 offset:7168
	s_sub_i32 s61, s60, s56
	s_waitcnt lgkmcnt(6)
	v_mfma_f32_32x32x16_bf16 v[32:47], v[80:83], v[64:67], 0
	v_mfma_f32_32x32x16_bf16 v[48:63], v[96:99], v[64:67], 0
	s_waitcnt lgkmcnt(4)
	v_mfma_f32_32x32x16_bf16 v[32:47], v[84:87], v[68:71], v[32:47]
	v_mfma_f32_32x32x16_bf16 v[48:63], v[100:103], v[68:71], v[48:63]
	s_waitcnt lgkmcnt(2)
	v_mfma_f32_32x32x16_bf16 v[32:47], v[88:91], v[72:75], v[32:47]
	v_mfma_f32_32x32x16_bf16 v[48:63], v[104:107], v[72:75], v[48:63]
	s_waitcnt lgkmcnt(0)
	v_mfma_f32_32x32x16_bf16 v[32:47], v[92:95], v[76:79], v[32:47]
	v_mfma_f32_32x32x16_bf16 v[48:63], v[108:111], v[76:79], v[48:63]
	v_add_u32_e32 v250, s64, v247
	ds_read_b64 v[146:147], v250 offset:8192
	ds_read_b64 v[148:149], v250 offset:8704
	ds_read_b64 v[150:151], v250 offset:9216
	ds_read_b64 v[152:153], v250 offset:9728
	ds_read_b64 v[154:155], v250 offset:10240
	ds_read_b64 v[156:157], v250 offset:10752
	ds_read_b64 v[158:159], v250 offset:11264
	ds_read_b64 v[160:161], v250 offset:11776
	ds_read_b64 v[162:163], v250 offset:12288
	ds_read_b64 v[164:165], v250 offset:12800
	ds_read_b64 v[166:167], v250 offset:13312
	ds_read_b64 v[168:169], v250 offset:13824
	ds_read_b64 v[170:171], v250 offset:14336
	ds_read_b64 v[172:173], v250 offset:14848
	ds_read_b64 v[174:175], v250 offset:15360
	ds_read_b64 v[176:177], v250 offset:15872
	s_cmp_ge_i32 s61, 50
	s_cbranch_scc1 .Lawin6_far
	s_lshl_b32 s23, s61, 5
	v_add_u32_e32 v241, s23, v222
	v_lshl_add_u32 v244, v241, 2, v242
	v_subrev_u32_e32 v245, 128, v244
	ds_read_b32 v224, v244 offset:108
	ds_read_b32 v225, v244 offset:104
	ds_read_b32 v226, v244 offset:100
	ds_read_b32 v227, v244 offset:96
	ds_read_b32 v228, v244 offset:76
	ds_read_b32 v229, v244 offset:72
	ds_read_b32 v230, v244 offset:68
	ds_read_b32 v231, v244 offset:64
	ds_read_b32 v232, v244 offset:44
	ds_read_b32 v233, v244 offset:40
	ds_read_b32 v234, v244 offset:36
	ds_read_b32 v235, v244 offset:32
	ds_read_b32 v236, v244 offset:12
	ds_read_b32 v237, v244 offset:8
	ds_read_b32 v238, v244 offset:4
	ds_read_b32 v239, v244 offset:0
	s_waitcnt lgkmcnt(8)
	v_add_f32_e32 v32, v32, v224
	v_add_f32_e32 v33, v33, v225
	v_add_f32_e32 v34, v34, v226
	v_add_f32_e32 v35, v35, v227
	v_add_f32_e32 v36, v36, v228
	v_add_f32_e32 v37, v37, v229
	v_add_f32_e32 v38, v38, v230
	v_add_f32_e32 v39, v39, v231
	s_waitcnt lgkmcnt(0)
	v_add_f32_e32 v40, v40, v232
	v_add_f32_e32 v41, v41, v233
	v_add_f32_e32 v42, v42, v234
	v_add_f32_e32 v43, v43, v235
	v_add_f32_e32 v44, v44, v236
	v_add_f32_e32 v45, v45, v237
	v_add_f32_e32 v46, v46, v238
	v_add_f32_e32 v47, v47, v239
	ds_read_b32 v224, v245 offset:108
	ds_read_b32 v225, v245 offset:104
	ds_read_b32 v226, v245 offset:100
	ds_read_b32 v227, v245 offset:96
	ds_read_b32 v228, v245 offset:76
	ds_read_b32 v229, v245 offset:72
	ds_read_b32 v230, v245 offset:68
	ds_read_b32 v231, v245 offset:64
	ds_read_b32 v232, v245 offset:44
	ds_read_b32 v233, v245 offset:40
	ds_read_b32 v234, v245 offset:36
	ds_read_b32 v235, v245 offset:32
	ds_read_b32 v236, v245 offset:12
	ds_read_b32 v237, v245 offset:8
	ds_read_b32 v238, v245 offset:4
	ds_read_b32 v239, v245 offset:0
	s_waitcnt lgkmcnt(8)
	v_add_f32_e32 v48, v48, v224
	v_add_f32_e32 v49, v49, v225
	v_add_f32_e32 v50, v50, v226
	v_add_f32_e32 v51, v51, v227
	v_add_f32_e32 v52, v52, v228
	v_add_f32_e32 v53, v53, v229
	v_add_f32_e32 v54, v54, v230
	v_add_f32_e32 v55, v55, v231
	s_waitcnt lgkmcnt(0)
	v_add_f32_e32 v56, v56, v232
	v_add_f32_e32 v57, v57, v233
	v_add_f32_e32 v58, v58, v234
	v_add_f32_e32 v59, v59, v235
	v_add_f32_e32 v60, v60, v236
	v_add_f32_e32 v61, v61, v237
	v_add_f32_e32 v62, v62, v238
	v_add_f32_e32 v63, v63, v239
	s_cmp_ge_i32 s61, 15
	s_cbranch_scc0 .Lawin6_nowin
	v_subrev_u32_e32 v246, 32, v241
	v_cmp_gt_i32_e32 vcc, 0x200, v241
	s_nop 1
	v_cndmask_b32_e32 v32, v199, v32, vcc
	v_cmp_gt_i32_e32 vcc, 0x201, v241
	s_nop 1
	v_cndmask_b32_e32 v33, v199, v33, vcc
	v_cmp_gt_i32_e32 vcc, 0x202, v241
	s_nop 1
	v_cndmask_b32_e32 v34, v199, v34, vcc
	v_cmp_gt_i32_e32 vcc, 0x203, v241
	s_nop 1
	v_cndmask_b32_e32 v35, v199, v35, vcc
	v_cmp_gt_i32_e32 vcc, 0x208, v241
	s_nop 1
	v_cndmask_b32_e32 v36, v199, v36, vcc
	v_cmp_gt_i32_e32 vcc, 0x209, v241
	s_nop 1
	v_cndmask_b32_e32 v37, v199, v37, vcc
	v_cmp_gt_i32_e32 vcc, 0x20a, v241
	s_nop 1
	v_cndmask_b32_e32 v38, v199, v38, vcc
	v_cmp_gt_i32_e32 vcc, 0x20b, v241
	s_nop 1
	v_cndmask_b32_e32 v39, v199, v39, vcc
	v_cmp_gt_i32_e32 vcc, 0x210, v241
	s_nop 1
	v_cndmask_b32_e32 v40, v199, v40, vcc
	v_cmp_gt_i32_e32 vcc, 0x211, v241
	s_nop 1
	v_cndmask_b32_e32 v41, v199, v41, vcc
	v_cmp_gt_i32_e32 vcc, 0x212, v241
	s_nop 1
	v_cndmask_b32_e32 v42, v199, v42, vcc
	v_cmp_gt_i32_e32 vcc, 0x213, v241
	s_nop 1
	v_cndmask_b32_e32 v43, v199, v43, vcc
	v_cmp_gt_i32_e32 vcc, 0x218, v241
	s_nop 1
	v_cndmask_b32_e32 v44, v199, v44, vcc
	v_cmp_gt_i32_e32 vcc, 0x219, v241
	s_nop 1
	v_cndmask_b32_e32 v45, v199, v45, vcc
	v_cmp_gt_i32_e32 vcc, 0x21a, v241
	s_nop 1
	v_cndmask_b32_e32 v46, v199, v46, vcc
	v_cmp_gt_i32_e32 vcc, 0x21b, v241
	s_nop 1
	v_cndmask_b32_e32 v47, v199, v47, vcc
	v_cmp_gt_i32_e32 vcc, 0x200, v246
	s_nop 1
	v_cndmask_b32_e32 v48, v199, v48, vcc
	v_cmp_gt_i32_e32 vcc, 0x201, v246
	s_nop 1
	v_cndmask_b32_e32 v49, v199, v49, vcc
	v_cmp_gt_i32_e32 vcc, 0x202, v246
	s_nop 1
	v_cndmask_b32_e32 v50, v199, v50, vcc
	v_cmp_gt_i32_e32 vcc, 0x203, v246
	s_nop 1
	v_cndmask_b32_e32 v51, v199, v51, vcc
	v_cmp_gt_i32_e32 vcc, 0x208, v246
	s_nop 1
	v_cndmask_b32_e32 v52, v199, v52, vcc
	v_cmp_gt_i32_e32 vcc, 0x209, v246
	s_nop 1
	v_cndmask_b32_e32 v53, v199, v53, vcc
	v_cmp_gt_i32_e32 vcc, 0x20a, v246
	s_nop 1
	v_cndmask_b32_e32 v54, v199, v54, vcc
	v_cmp_gt_i32_e32 vcc, 0x20b, v246
	s_nop 1
	v_cndmask_b32_e32 v55, v199, v55, vcc
	v_cmp_gt_i32_e32 vcc, 0x210, v246
	s_nop 1
	v_cndmask_b32_e32 v56, v199, v56, vcc
	v_cmp_gt_i32_e32 vcc, 0x211, v246
	s_nop 1
	v_cndmask_b32_e32 v57, v199, v57, vcc
	v_cmp_gt_i32_e32 vcc, 0x212, v246
	s_nop 1
	v_cndmask_b32_e32 v58, v199, v58, vcc
	v_cmp_gt_i32_e32 vcc, 0x213, v246
	s_nop 1
	v_cndmask_b32_e32 v59, v199, v59, vcc
	v_cmp_gt_i32_e32 vcc, 0x218, v246
	s_nop 1
	v_cndmask_b32_e32 v60, v199, v60, vcc
	v_cmp_gt_i32_e32 vcc, 0x219, v246
	s_nop 1
	v_cndmask_b32_e32 v61, v199, v61, vcc
	v_cmp_gt_i32_e32 vcc, 0x21a, v246
	s_nop 1
	v_cndmask_b32_e32 v62, v199, v62, vcc
	v_cmp_gt_i32_e32 vcc, 0x21b, v246
	s_nop 1
	v_cndmask_b32_e32 v63, v199, v63, vcc

; template <class KP, class VP, class ACT, class FILL>
; DI void attn_loop(AttnSt& st, const bf16x8 (&qf)[4], int k0, int k1, size_t vstride, KP kp, VP vp, ACT act, FILL fill) {
;     ...
;   for (int kt = k0; kt <= k1; ++kt) {
.Lawin6_skip:
	s_add_u32 s64, s64, 0x4000
	s_cmp_eq_u32 s64, 0x20000
	s_cselect_b32 s64, 0x10000, s64
	s_add_u32 s56, s56, 2
	s_cmp_le_u32 s56, s59
	s_cbranch_scc1 .Lawin6_loop
	s_nop 15
	s_waitcnt vmcnt(0)

; #define NEGINF (-__builtin_inff())
; #define TIDX get_tid_()
; DI int crow(int i, int h) { return (i & 3) + 8 * (i >> 2) + 4 * h; }
; DI void nsa_win_item(const Params& p, int b, int head, int qb, const unsigned char* blut, const float* tbl) {
;   const int lane = TIDX & 63, r = lane & 31, h = lane >> 5;
;   const int g = head / 3, bg = b * 2 + g;
;   const int t = qb * 32 + r;
;   const float* tblh = tbl + head * 32;
;   bf16x8 qf[4];
;   load_q(qf, (const bf16_t*)(p.ws + OFF_QN) + (size_t)(b * 4096 + t) * 384 + head * 64 + 8 * h);
;   const float g2 = ((const float*)(p.ws + OFF_GATES))[(size_t)(b * 4096 + t) * 18 + head * 3 + 2];
;   f32x16 y0, y1;
; #pragma unroll
;   for (int i = 0; i < 16; ++i) { y0[i] = 0.f; y1[i] = 0.f; }
;   {
;     const bf16_t* K = (const bf16_t*)(p.ws + OFF_KWIN) + (size_t)bg * 4096 * 64;
;     const bf16_t* Vt = (const bf16_t*)(p.ws + OFF_VWINT) + (size_t)bg * 64 * 4096;
;     AttnSt st; attn_init(st);
;     const int k0 = qb >= 16 ? qb - 16 : 0;
;     attn_loop(st, qf, k0, qb, 32,
;       [&](int kt) { return K + (size_t)kt * 2048 + (h * 32 + r) * 8; },
;       [&](int kt) { return Vt + (size_t)kt * 2048 + (h * 32 + r) * 4; },
;       [&](int kt) { return true; },
;       [&](int kt, const f32x16& s, float (&lg)[16]) {
;         int dist[16]; float bv[16];
; #pragma unroll
;         for (int i = 0; i < 16; ++i) dist[i] = t - (kt * 32 + crow(i, h));
;         bias16(blut, tblh, dist, bv);
; #pragma unroll
;         for (int i = 0; i < 16; ++i) lg[i] = (dist[i] >= 0 && dist[i] < 512) ? s[i] + bv[i] : NEGINF;
;       });
; DI void filler_items(const Params& p, int layer, char* lds, int which) {
;     ...
;     if (which == 0) {
;       if (item >= 128 * 16 + 96 * 48) break;
;       if (item < 128 * 16) { const int qb = 127 - item / 16, sub = item % 16; dil_item(p, sub >> 1, sub & 1, qb, blut, tbl); }
;       else { const int it2 = item - 128 * 16, qb = 127 - it2 / 48, sub = it2 % 48; nsa_win_item(p, sub / 6, sub % 6, qb, blut, tbl); }
.Lf4_done:
	v_mov_b32_e32 v4, s14
	s_movk_i32 s8, 0x1a00
	s_waitcnt lgkmcnt(0)
	v_cmp_gt_i32_e32 vcc, s8, v4
	s_mov_b64 s[8:9], -1
	s_and_saveexec_b64 s[14:15], vcc
	s_cbranch_execz .LBB0_1024
	s_movk_i32 s8, 0x7ff
	v_cmp_lt_i32_e32 vcc, s8, v4
	s_and_saveexec_b64 s[8:9], vcc
	s_xor_b64 s[8:9], exec, s[8:9]
	s_cbranch_execz .LBB0_1039
	v_add_u16_e32 v0, 0xf800, v4
	v_mul_u32_u24_e32 v1, 0xaaab, v0
	v_lshrrev_b32_e32 v30, 21, v1
	s_movk_i32 s23, 0x7f
	v_mul_lo_u16_e32 v1, 48, v30
	v_sub_u32_sdwa v138, s23, v30 dst_sel:DWORD dst_unused:UNUSED_PAD src0_sel:DWORD src1_sel:WORD_0
	v_sub_u16_e32 v0, v0, v1
	s_movk_i32 s23, 0xab
	v_mul_lo_u16_sdwa v1, v0, s23 dst_sel:DWORD dst_unused:UNUSED_PAD src0_sel:BYTE_0 src1_sel:DWORD
	v_lshrrev_b16_e32 v2, 10, v1
	v_mul_lo_u16_e32 v1, 6, v2
	v_sub_u16_e32 v31, v0, v1
	v_mov_b32_e32 v0, v129
	v_readlane_b32 s24, v253, 13
	v_and_b32_e32 v32, 31, v0
	v_bfe_u32 v33, v0, 5, 1
	v_lshlrev_b32_e32 v0, 5, v138
	v_lshlrev_b32_e32 v1, 12, v2
	v_readlane_b32 s25, v253, 14
	v_or3_b32 v113, v32, v0, v1
	s_movk_i32 s23, 0x300
	v_mov_b64_e32 v[0:1], s[24:25]
	v_mad_u64_u32 v[0:1], s[26:27], v113, s23, v[0:1]
	v_lshlrev_b32_sdwa v130, v202, v31 dst_sel:DWORD dst_unused:UNUSED_PAD src0_sel:DWORD src1_sel:BYTE_0
	v_cmp_gt_u16_sdwa vcc, v31, v204 src0_sel:BYTE_0 src1_sel:DWORD
	v_lshl_add_u64 v[4:5], v[0:1], 0, v[130:131]
	v_readlane_b32 s24, v253, 31
	v_cndmask_b32_e32 v0, 0, v205, vcc
	v_add_u32_e32 v139, 0, v130
	v_lshl_or_b32 v130, v2, 20, v0
	v_readlane_b32 s25, v253, 32
	s_movk_i32 s23, 0x6f
	v_sub_u32_sdwa v0, s23, v30 dst_sel:DWORD dst_unused:UNUSED_PAD src0_sel:DWORD src1_sel:WORD_0
	v_lshl_add_u64 v[20:21], s[24:25], 0, v[130:131]
	v_readlane_b32 s24, v253, 33
	v_readlane_b32 s25, v253, 34
	v_lshlrev_b32_e32 v2, 3, v32
	v_lshl_or_b32 v24, v33, 8, v2
	v_lshl_add_u64 v[22:23], s[24:25], 0, v[130:131]
	v_lshlrev_b32_e32 v130, 12, v0
	v_lshl_add_u64 v[0:1], v[20:21], 0, v[130:131]
	v_lshlrev_b32_e32 v26, 1, v24
	v_mov_b32_e32 v27, v131
	v_lshl_add_u64 v[12:13], v[0:1], 0, v[26:27]
	global_load_dwordx4 v[0:3], v[12:13], off
	v_lshlrev_b32_e32 v6, 4, v33
	v_mov_b32_e32 v7, v131
	v_lshl_add_u64 v[14:15], v[4:5], 0, v[6:7]
	global_load_dwordx4 v[64:67], v[14:15], off
	global_load_dwordx4 v[68:71], v[14:15], off offset:32
	global_load_dwordx4 v[4:7], v[12:13], off offset:1024
	v_readlane_b32 s24, v253, 29
	v_readlane_b32 s25, v253, 30
	v_lshlrev_b32_sdwa v10, v209, v30 dst_sel:DWORD dst_unused:UNUSED_PAD src0_sel:DWORD src1_sel:WORD_0
	v_sub_u32_e32 v16, 0x70000, v10
	v_mov_b64_e32 v[8:9], s[24:25]
	v_mul_u32_u24_sdwa v10, v31, v203 dst_sel:DWORD dst_unused:UNUSED_PAD src0_sel:BYTE_0 src1_sel:DWORD
	s_movk_i32 s23, 0x48
	v_mov_b32_e32 v11, v131
	v_mad_u64_u32 v[8:9], s[26:27], v113, s23, v[8:9]
	v_lshlrev_b32_e32 v10, 2, v10
	v_lshl_add_u64 v[18:19], v[8:9], 0, v[10:11]
	global_load_dwordx4 v[8:11], v[12:13], off offset:2048
	global_load_dwordx4 v[72:75], v[14:15], off offset:64
	global_load_dwordx4 v[76:79], v[14:15], off offset:96
	v_mov_b32_e32 v17, v131
	v_lshl_add_u64 v[14:15], v[20:21], 0, v[16:17]
	v_mov_b32_e32 v25, v131
	v_lshl_add_u64 v[16:17], v[22:23], 0, v[130:131]
	v_lshl_add_u64 v[14:15], v[14:15], 0, v[26:27]
	v_lshl_add_u64 v[28:29], v[16:17], 0, v[24:25]
	global_load_dword v140, v[18:19], off
	s_nop 0
	global_load_dwordx4 v[16:19], v[12:13], off offset:3072
	global_load_dwordx4 v[88:91], v[14:15], off offset:2048
	global_load_dwordx4 v[84:87], v[14:15], off offset:1024
	global_load_dwordx4 v[92:95], v[14:15], off
	global_load_dwordx2 v[82:83], v[28:29], off offset:3584
	global_load_dwordx2 v[80:81], v[28:29], off offset:3072
	global_load_dwordx2 v[98:99], v[28:29], off offset:2560
	global_load_dwordx2 v[96:97], v[28:29], off offset:2048
	global_load_dwordx2 v[106:107], v[28:29], off offset:1536
	global_load_dwordx2 v[104:105], v[28:29], off offset:1024
	global_load_dwordx2 v[110:111], v[28:29], off offset:512
	global_load_dwordx4 v[100:103], v[14:15], off offset:3072
	global_load_dwordx2 v[108:109], v[28:29], off
	s_mov_b32 s56, 0
	s_mov_b32 s57, s56
	s_mov_b32 s58, s56
	s_mov_b32 s59, s56
	s_mov_b32 s60, s56
	s_mov_b32 s61, s56
	s_mov_b32 s62, s56
	s_mov_b32 s63, s56
	s_mov_b32 s64, s56
	s_mov_b32 s65, s56
	s_mov_b32 s66, s56
	s_mov_b32 s67, s56
	s_mov_b32 s68, s56
	s_mov_b32 s69, s56
	s_mov_b32 s70, s56
	s_mov_b32 s71, s56
	s_movk_i32 s23, 0x71
	v_lshlrev_b32_sdwa v112, v201, v31 dst_sel:DWORD dst_unused:UNUSED_PAD src0_sel:DWORD src1_sel:BYTE_0
	v_lshl_add_u64 v[114:115], v[22:23], 0, v[24:25]
	v_lshl_add_u64 v[116:117], v[20:21], 0, v[26:27]
	v_lshlrev_b32_e32 v141, 2, v33
	v_sub_u32_sdwa v143, s23, v30 dst_sel:DWORD dst_unused:UNUSED_PAD src0_sel:DWORD src1_sel:WORD_0
	v_sub_u32_e32 v142, v32, v141
	v_mov_b32_e32 v144, 0
	v_mov_b32_e32 v145, 0xff800000
	s_waitcnt vmcnt(19)
	v_mfma_f32_32x32x16_bf16 v[48:63], v[0:3], v[64:67], 0
	s_waitcnt vmcnt(17)
	v_mfma_f32_32x32x16_bf16 v[48:63], v[4:7], v[68:71], v[48:63]
	s_waitcnt vmcnt(15)
	v_mfma_f32_32x32x16_bf16 v[48:63], v[8:11], v[72:75], v[48:63]
	v_mov_b64_e32 v[0:1], s[56:57]
	v_mov_b64_e32 v[14:15], s[70:71]
	v_mov_b64_e32 v[2:3], s[58:59]
	v_mov_b64_e32 v[4:5], s[60:61]
	v_mov_b64_e32 v[6:7], s[62:63]
	v_mov_b64_e32 v[8:9], s[64:65]
	v_mov_b64_e32 v[10:11], s[66:67]
	s_waitcnt vmcnt(12)
	v_mfma_f32_32x32x16_bf16 v[48:63], v[16:19], v[76:79], v[48:63]
	v_mov_b64_e32 v[12:13], s[68:69]
	v_mov_b64_e32 v[30:31], v[14:15]
	v_mov_b64_e32 v[28:29], v[12:13]
	v_mov_b64_e32 v[26:27], v[10:11]
	v_mov_b64_e32 v[24:25], v[8:9]
	v_mov_b64_e32 v[22:23], v[6:7]
	v_mov_b64_e32 v[20:21], v[4:5]
	v_mov_b64_e32 v[18:19], v[2:3]
	v_mov_b64_e32 v[16:17], v[0:1]
	s_waitcnt vmcnt(0)
	v_readfirstlane_b32 s60, v138
	v_lshrrev_b32_e32 v184, 6, v129
	v_and_b32_e32 v185, 63, v129
	v_lshlrev_b32_e32 v185, 3, v185
	v_readfirstlane_b32 s58, v184
	s_sub_u32 s65, s60, 16
	s_cmp_lt_u32 s60, 16
	s_cselect_b32 s65, 0, s65
	s_mov_b64 s[62:63], -1
	v_mov_b32_e32 v32, s60
	v_mov_b32_e32 v33, 0x1940
	v_lshl_add_u32 v42, v184, 2, v33
	ds_write_b32 v42, v32
	s_waitcnt lgkmcnt(0)
	s_barrier
; #define MFMA32(a, b, c) __builtin_amdgcn_mfma_f32_32x32x16_bf16((a), (b), (c), 0, 0, 0)
; template <class KP, class VP, class ACT, class FILL>
; DI void attn_loop(AttnSt& st, const bf16x8 (&qf)[4], int k0, int k1, size_t vstride, KP kp, VP vp, ACT act, FILL fill) {
;   KVT cur, nxt;
;   {
;     KVT t0; load_kv(t0, kp(k0), vp(k0), vstride);
; #pragma unroll
;     for (int i = 0; i < 8; ++i) cur.v[i] = t0.v[i];
; #pragma unroll
;     for (int i = 0; i < 4; ++i) cur.k[i] = t0.k[i];
;   }
;   f32x16 s_cur;
;   { const float z = 0.f;
; #pragma unroll
;     for (int i = 0; i < 16; ++i) s_cur[i] = z; }
; #pragma unroll
;   for (int ss = 0; ss < 4; ++ss) s_cur = MFMA32(cur.k[ss], qf[ss], s_cur);
;   {
;     const int kn = (k0 < k1) ? k0 + 1 : k1;
;     const bf16_t* krow = kp(kn);
; #pragma unroll
;     for (int ss = 0; ss < 4; ++ss) nxt.k[ss] = *(const bf16x8*)(krow + 512 * ss);
;   }
; DI void bias16(const unsigned char* blut, const float* tblh, const int (&dist)[16], float (&bv)[16]) {
;   int bk[16];
; #pragma unroll
;   for (int i = 0; i < 16; ++i) { const int d = dist[i] < 0 ? 0 : (dist[i] > 2048 ? 2048 : dist[i]); bk[i] = blut[d]; }
; #pragma unroll
;   for (int i = 0; i < 16; ++i) asm volatile("" : "+v"(bk[i]));
; #pragma unroll
;   for (int i = 0; i < 16; ++i) bv[i] = tblh[bk[i]];
; #pragma unroll
;   for (int i = 0; i < 16; ++i) asm volatile("" : "+v"(bv[i]));
; }
	ds_read_b128 v[34:37], v33
	ds_read_b128 v[38:41], v33 offset:16
	s_waitcnt lgkmcnt(0)
	v_min3_u32 v42, v34, v35, v36
	v_min3_u32 v42, v42, v37, v38
	v_min3_u32 v42, v42, v39, v40
	v_min_u32_e32 v42, v42, v41
	v_max3_u32 v34, v34, v35, v36
	v_max3_u32 v34, v34, v37, v38
	v_max3_u32 v34, v34, v39, v40
	v_max_u32_e32 v34, v34, v41
	s_nop 0
	v_readfirstlane_b32 s59, v34
	v_readfirstlane_b32 s66, v42
	s_sub_u32 s56, s66, 16
	s_cmp_lt_u32 s66, 16
	s_cselect_b32 s56, 0, s56
	s_and_b32 s56, s56, -2
	s_lshr_b32 s23, s56, 1
	s_mov_b32 s64, 0x10000
	s_lshr_b32 s24, s59, 1
	s_min_u32 s24, s23, s24
	s_lshl_b32 s26, s24, 13
	s_lshl_b32 s24, s58, 10
	s_add_u32 s26, s26, s24
	s_mov_b32 s27, 0
	v_lshl_add_u64 v[186:187], v[116:117], 0, s[26:27]
	v_lshl_add_u64 v[126:127], v[114:115], 0, s[26:27]
	v_add_co_u32_e32 v126, vcc, v126, v185
	v_addc_co_u32_e32 v127, vcc, 0, v127, vcc
	s_add_u32 s24, s24, s64
	s_mov_b32 m0, s24
	s_nop 0
	global_load_lds_dwordx4 v[186:187], off
	s_add_u32 s24, s24, 0x2000
	s_mov_b32 m0, s24
	s_nop 0
	global_load_lds_dwordx4 v[126:127], off
	s_lshr_b32 s23, s56, 1
	s_add_u32 s23, s23, 1
	s_mov_b32 s64, 0x14000
	s_lshr_b32 s24, s59, 1
	s_min_u32 s24, s23, s24
	s_lshl_b32 s26, s24, 13
	s_lshl_b32 s24, s58, 10
	s_add_u32 s26, s26, s24
	s_mov_b32 s27, 0
	v_lshl_add_u64 v[186:187], v[116:117], 0, s[26:27]
	v_lshl_add_u64 v[126:127], v[114:115], 0, s[26:27]
	v_add_co_u32_e32 v126, vcc, v126, v185
	v_addc_co_u32_e32 v127, vcc, 0, v127, vcc
	s_add_u32 s24, s24, s64
	s_mov_b32 m0, s24
	s_nop 0
	global_load_lds_dwordx4 v[186:187], off
	s_add_u32 s24, s24, 0x2000
	s_mov_b32 m0, s24
	s_nop 0
	global_load_lds_dwordx4 v[126:127], off
	s_mov_b32 s64, 0x10000
	v_lshrrev_b32_e32 v184, 6, v129
	v_mul_u32_u24_e32 v184, 6912, v184
	v_add_u32_e32 v180, 8192, v184
	v_and_b32_e32 v184, 63, v129
	v_mov_b32_e32 v80, 0
	v_mov_b32_e32 v81, v184
	v_add_u32_e32 v82, 64, v184
	v_add_u32_e32 v83, 128, v184
	v_add_u32_e32 v84, 192, v184
	v_add_u32_e32 v85, 256, v184
	v_add_u32_e32 v86, 320, v184
	v_add_u32_e32 v87, 384, v184
	v_add_u32_e32 v88, 448, v184
	v_add_u32_e32 v89, 512, v184
	ds_read_u8 v80, v80
	ds_read_u8 v81, v81
	ds_read_u8 v82, v82
	ds_read_u8 v83, v83
	ds_read_u8 v84, v84
	ds_read_u8 v85, v85
	ds_read_u8 v86, v86
	ds_read_u8 v87, v87
	ds_read_u8 v88, v88
	ds_read_u8 v89, v89
	s_waitcnt lgkmcnt(9)
	v_lshl_add_u32 v80, v80, 2, v139
	s_waitcnt lgkmcnt(8)
	v_lshl_add_u32 v81, v81, 2, v139
	s_waitcnt lgkmcnt(7)
	v_lshl_add_u32 v82, v82, 2, v139
	s_waitcnt lgkmcnt(6)
	v_lshl_add_u32 v83, v83, 2, v139
	s_waitcnt lgkmcnt(5)
	v_lshl_add_u32 v84, v84, 2, v139
	s_waitcnt lgkmcnt(4)
	v_lshl_add_u32 v85, v85, 2, v139
	s_waitcnt lgkmcnt(3)
	v_lshl_add_u32 v86, v86, 2, v139
	s_waitcnt lgkmcnt(2)
	v_lshl_add_u32 v87, v87, 2, v139
	s_waitcnt lgkmcnt(1)
	v_lshl_add_u32 v88, v88, 2, v139
	s_waitcnt lgkmcnt(0)
	v_lshl_add_u32 v89, v89, 2, v139
	ds_read_b32 v80, v80 offset:4096
	ds_read_b32 v81, v81 offset:4096
	ds_read_b32 v82, v82 offset:4096
	ds_read_b32 v83, v83 offset:4096
	ds_read_b32 v84, v84 offset:4096
	ds_read_b32 v85, v85 offset:4096
	ds_read_b32 v86, v86 offset:4096
	ds_read_b32 v87, v87 offset:4096
	ds_read_b32 v88, v88 offset:4096
	ds_read_b32 v89, v89 offset:4096
	v_lshl_add_u32 v182, v184, 2, v180
	s_waitcnt lgkmcnt(9)
	ds_write_b32 v182, v80 offset:0
	s_waitcnt lgkmcnt(9)
	ds_write_b32 v182, v81 offset:256
	s_waitcnt lgkmcnt(9)
	ds_write_b32 v182, v82 offset:512
	s_waitcnt lgkmcnt(9)
	ds_write_b32 v182, v83 offset:768
	s_waitcnt lgkmcnt(9)
	ds_write_b32 v182, v84 offset:1024
	s_waitcnt lgkmcnt(9)
	ds_write_b32 v182, v85 offset:1280
	s_waitcnt lgkmcnt(9)
	ds_write_b32 v182, v86 offset:1536
	s_waitcnt lgkmcnt(9)
	ds_write_b32 v182, v87 offset:1792
	s_waitcnt lgkmcnt(9)
	ds_write_b32 v182, v88 offset:2048
	s_waitcnt lgkmcnt(9)
	ds_write_b32 v182, v89 offset:2304
	ds_read_b32 v178, v139 offset:4220
	v_add_u32_e32 v180, 148, v180
	v_mov_b32_e32 v181, 0x7f800000
	s_waitcnt lgkmcnt(0)
.Lawin4_loop:
	s_lshr_b32 s23, s56, 1
	s_add_u32 s23, s23, 2
	s_add_u32 s61, s64, 0x8000
	s_sub_u32 s24, s61, 0x10000
	s_cmp_ge_u32 s61, 0x20000
	s_cselect_b32 s61, s24, s61
	s_lshr_b32 s24, s59, 1
	s_min_u32 s24, s23, s24
	s_lshl_b32 s26, s24, 13
	s_lshl_b32 s24, s58, 10
	s_add_u32 s26, s26, s24
	s_mov_b32 s27, 0
	v_lshl_add_u64 v[186:187], v[116:117], 0, s[26:27]
	v_lshl_add_u64 v[126:127], v[114:115], 0, s[26:27]
	v_add_co_u32_e32 v126, vcc, v126, v185
	v_addc_co_u32_e32 v127, vcc, 0, v127, vcc
	s_add_u32 s24, s24, s61
	s_mov_b32 m0, s24
	s_nop 0
	global_load_lds_dwordx4 v[186:187], off
	s_add_u32 s24, s24, 0x2000
	s_mov_b32 m0, s24
	s_nop 0
	global_load_lds_dwordx4 v[126:127], off
	s_waitcnt vmcnt(4)
	s_barrier
	s_cmp_le_u32 s56, s60
	s_cbranch_scc0 .Lawin4_skip
	s_add_u32 s24, s56, 1
	s_cmp_ge_u32 s24, s65
	s_cbranch_scc0 .Lawin4_skip
; #define MFMA32(a, b, c) __builtin_amdgcn_mfma_f32_32x32x16_bf16((a), (b), (c), 0, 0, 0)
; #define NEGINF (-__builtin_inff())
; DI int crow(int i, int h) { return (i & 3) + 8 * (i >> 2) + 4 * h; }
; DI f32x16 qk_tile(const bf16x8 (&qf)[4], const bf16_t* krow) {
;   f32x16 s;
; #pragma unroll
;   for (int i = 0; i < 16; ++i) s[i] = 0.f;
; #pragma unroll
;   for (int ss = 0; ss < 4; ++ss) { const bf16x8 kf = *(const bf16x8*)(krow + 512 * ss); s = MFMA32(kf, qf[ss], s); }
;   return s;
; }
; DI void nsa_win_item(const Params& p, int b, int head, int qb, const unsigned char* blut, const float* tbl) {
;     ...
;     attn_loop(st, qf, k0, qb, 32,
;       [&](int kt) { return K + (size_t)kt * 2048 + (h * 32 + r) * 8; },
;       [&](int kt) { return Vt + (size_t)kt * 2048 + (h * 32 + r) * 4; },
;       [&](int kt) { return true; },
;       [&](int kt, const f32x16& s, float (&lg)[16]) {
;         int dist[16]; float bv[16];
; #pragma unroll
;         for (int i = 0; i < 16; ++i) dist[i] = t - (kt * 32 + crow(i, h));
;         bias16(blut, tblh, dist, bv);
; #pragma unroll
;         for (int i = 0; i < 16; ++i) lg[i] = (dist[i] >= 0 && dist[i] < 512) ? s[i] + bv[i] : NEGINF;
;       });
	v_lshl_add_u32 v186, v185, 1, s64
	ds_read_b128 v[80:83], v186 offset:0
	ds_read_b128 v[96:99], v186 offset:4096
	ds_read_b128 v[84:87], v186 offset:1024
	ds_read_b128 v[100:103], v186 offset:5120
	ds_read_b128 v[88:91], v186 offset:2048
	ds_read_b128 v[104:107], v186 offset:6144
	ds_read_b128 v[92:95], v186 offset:3072
	ds_read_b128 v[108:111], v186 offset:7168
	s_sub_i32 s61, s60, s56
	s_waitcnt lgkmcnt(6)
	v_mfma_f32_32x32x16_bf16 v[32:47], v[80:83], v[64:67], 0
	v_mfma_f32_32x32x16_bf16 v[48:63], v[96:99], v[64:67], 0
	s_waitcnt lgkmcnt(4)
	v_mfma_f32_32x32x16_bf16 v[32:47], v[84:87], v[68:71], v[32:47]
	v_mfma_f32_32x32x16_bf16 v[48:63], v[100:103], v[68:71], v[48:63]
	s_waitcnt lgkmcnt(2)
	v_mfma_f32_32x32x16_bf16 v[32:47], v[88:91], v[72:75], v[32:47]
	v_mfma_f32_32x32x16_bf16 v[48:63], v[104:107], v[72:75], v[48:63]
	s_waitcnt lgkmcnt(0)
	v_mfma_f32_32x32x16_bf16 v[32:47], v[92:95], v[76:79], v[32:47]
	v_mfma_f32_32x32x16_bf16 v[48:63], v[108:111], v[76:79], v[48:63]
	v_add_u32_e32 v126, s64, v185
	ds_read_b64 v[146:147], v126 offset:8192
	ds_read_b64 v[148:149], v126 offset:8704
	ds_read_b64 v[150:151], v126 offset:9216
	ds_read_b64 v[152:153], v126 offset:9728
	ds_read_b64 v[154:155], v126 offset:10240
	ds_read_b64 v[156:157], v126 offset:10752
	ds_read_b64 v[158:159], v126 offset:11264
	ds_read_b64 v[160:161], v126 offset:11776
	ds_read_b64 v[162:163], v126 offset:12288
	ds_read_b64 v[164:165], v126 offset:12800
	ds_read_b64 v[166:167], v126 offset:13312
	ds_read_b64 v[168:169], v126 offset:13824
	ds_read_b64 v[170:171], v126 offset:14336
	ds_read_b64 v[172:173], v126 offset:14848
	ds_read_b64 v[174:175], v126 offset:15360
	ds_read_b64 v[176:177], v126 offset:15872
	s_cmp_ge_i32 s61, 50
	s_cbranch_scc1 .Lawin4_far
	s_lshl_b32 s23, s61, 5
	v_add_u32_e32 v179, s23, v142
	v_lshl_add_u32 v182, v179, 2, v180
	v_subrev_u32_e32 v183, 128, v182
	ds_read_b32 v118, v182 offset:108
	ds_read_b32 v119, v182 offset:104
	ds_read_b32 v120, v182 offset:100
	ds_read_b32 v121, v182 offset:96
	ds_read_b32 v122, v182 offset:76
	ds_read_b32 v123, v182 offset:72
	ds_read_b32 v124, v182 offset:68
	ds_read_b32 v125, v182 offset:64
	ds_read_b32 v132, v182 offset:44
	ds_read_b32 v133, v182 offset:40
	ds_read_b32 v134, v182 offset:36
	ds_read_b32 v135, v182 offset:32
	ds_read_b32 v218, v182 offset:12
	ds_read_b32 v219, v182 offset:8
	ds_read_b32 v220, v182 offset:4
	ds_read_b32 v221, v182 offset:0
	s_waitcnt lgkmcnt(8)
	v_add_f32_e32 v32, v32, v118
	v_add_f32_e32 v33, v33, v119
	v_add_f32_e32 v34, v34, v120
	v_add_f32_e32 v35, v35, v121
	v_add_f32_e32 v36, v36, v122
	v_add_f32_e32 v37, v37, v123
	v_add_f32_e32 v38, v38, v124
	v_add_f32_e32 v39, v39, v125
	s_waitcnt lgkmcnt(0)
	v_add_f32_e32 v40, v40, v132
	v_add_f32_e32 v41, v41, v133
	v_add_f32_e32 v42, v42, v134
	v_add_f32_e32 v43, v43, v135
	v_add_f32_e32 v44, v44, v218
	v_add_f32_e32 v45, v45, v219
	v_add_f32_e32 v46, v46, v220
	v_add_f32_e32 v47, v47, v221
	ds_read_b32 v118, v183 offset:108
	ds_read_b32 v119, v183 offset:104
	ds_read_b32 v120, v183 offset:100
	ds_read_b32 v121, v183 offset:96
	ds_read_b32 v122, v183 offset:76
	ds_read_b32 v123, v183 offset:72
	ds_read_b32 v124, v183 offset:68
	ds_read_b32 v125, v183 offset:64
	ds_read_b32 v132, v183 offset:44
	ds_read_b32 v133, v183 offset:40
	ds_read_b32 v134, v183 offset:36
	ds_read_b32 v135, v183 offset:32
	ds_read_b32 v218, v183 offset:12
	ds_read_b32 v219, v183 offset:8
	ds_read_b32 v220, v183 offset:4
	ds_read_b32 v221, v183 offset:0
	s_waitcnt lgkmcnt(8)
	v_add_f32_e32 v48, v48, v118
	v_add_f32_e32 v49, v49, v119
	v_add_f32_e32 v50, v50, v120
	v_add_f32_e32 v51, v51, v121
	v_add_f32_e32 v52, v52, v122
	v_add_f32_e32 v53, v53, v123
	v_add_f32_e32 v54, v54, v124
	v_add_f32_e32 v55, v55, v125
	s_waitcnt lgkmcnt(0)
	v_add_f32_e32 v56, v56, v132
	v_add_f32_e32 v57, v57, v133
	v_add_f32_e32 v58, v58, v134
	v_add_f32_e32 v59, v59, v135
	v_add_f32_e32 v60, v60, v218
	v_add_f32_e32 v61, v61, v219
	v_add_f32_e32 v62, v62, v220
	v_add_f32_e32 v63, v63, v221
	s_cmp_ge_i32 s61, 15
	s_cbranch_scc0 .Lawin4_nowin
	v_subrev_u32_e32 v184, 32, v179
	v_cmp_gt_i32_e32 vcc, 0x200, v179
	s_nop 1
	v_cndmask_b32_e32 v32, v199, v32, vcc
	v_cmp_gt_i32_e32 vcc, 0x201, v179
	s_nop 1
	v_cndmask_b32_e32 v33, v199, v33, vcc
	v_cmp_gt_i32_e32 vcc, 0x202, v179
	s_nop 1
	v_cndmask_b32_e32 v34, v199, v34, vcc
	v_cmp_gt_i32_e32 vcc, 0x203, v179
	s_nop 1
	v_cndmask_b32_e32 v35, v199, v35, vcc
	v_cmp_gt_i32_e32 vcc, 0x208, v179
	s_nop 1
	v_cndmask_b32_e32 v36, v199, v36, vcc
	v_cmp_gt_i32_e32 vcc, 0x209, v179
	s_nop 1
	v_cndmask_b32_e32 v37, v199, v37, vcc
	v_cmp_gt_i32_e32 vcc, 0x20a, v179
	s_nop 1
	v_cndmask_b32_e32 v38, v199, v38, vcc
	v_cmp_gt_i32_e32 vcc, 0x20b, v179
	s_nop 1
	v_cndmask_b32_e32 v39, v199, v39, vcc
	v_cmp_gt_i32_e32 vcc, 0x210, v179
	s_nop 1
	v_cndmask_b32_e32 v40, v199, v40, vcc
	v_cmp_gt_i32_e32 vcc, 0x211, v179
	s_nop 1
	v_cndmask_b32_e32 v41, v199, v41, vcc
	v_cmp_gt_i32_e32 vcc, 0x212, v179
	s_nop 1
	v_cndmask_b32_e32 v42, v199, v42, vcc
	v_cmp_gt_i32_e32 vcc, 0x213, v179
	s_nop 1
	v_cndmask_b32_e32 v43, v199, v43, vcc
	v_cmp_gt_i32_e32 vcc, 0x218, v179
	s_nop 1
	v_cndmask_b32_e32 v44, v199, v44, vcc
	v_cmp_gt_i32_e32 vcc, 0x219, v179
	s_nop 1
	v_cndmask_b32_e32 v45, v199, v45, vcc
	v_cmp_gt_i32_e32 vcc, 0x21a, v179
	s_nop 1
	v_cndmask_b32_e32 v46, v199, v46, vcc
	v_cmp_gt_i32_e32 vcc, 0x21b, v179
	s_nop 1
	v_cndmask_b32_e32 v47, v199, v47, vcc
	v_cmp_gt_i32_e32 vcc, 0x200, v184
	s_nop 1
	v_cndmask_b32_e32 v48, v199, v48, vcc
	v_cmp_gt_i32_e32 vcc, 0x201, v184
	s_nop 1
	v_cndmask_b32_e32 v49, v199, v49, vcc
	v_cmp_gt_i32_e32 vcc, 0x202, v184
	s_nop 1
	v_cndmask_b32_e32 v50, v199, v50, vcc
	v_cmp_gt_i32_e32 vcc, 0x203, v184
	s_nop 1
	v_cndmask_b32_e32 v51, v199, v51, vcc
	v_cmp_gt_i32_e32 vcc, 0x208, v184
	s_nop 1
	v_cndmask_b32_e32 v52, v199, v52, vcc
	v_cmp_gt_i32_e32 vcc, 0x209, v184
	s_nop 1
	v_cndmask_b32_e32 v53, v199, v53, vcc
	v_cmp_gt_i32_e32 vcc, 0x20a, v184
	s_nop 1
	v_cndmask_b32_e32 v54, v199, v54, vcc
	v_cmp_gt_i32_e32 vcc, 0x20b, v184
	s_nop 1
	v_cndmask_b32_e32 v55, v199, v55, vcc
	v_cmp_gt_i32_e32 vcc, 0x210, v184
	s_nop 1
	v_cndmask_b32_e32 v56, v199, v56, vcc
	v_cmp_gt_i32_e32 vcc, 0x211, v184
	s_nop 1
	v_cndmask_b32_e32 v57, v199, v57, vcc
	v_cmp_gt_i32_e32 vcc, 0x212, v184
	s_nop 1
	v_cndmask_b32_e32 v58, v199, v58, vcc
	v_cmp_gt_i32_e32 vcc, 0x213, v184
	s_nop 1
	v_cndmask_b32_e32 v59, v199, v59, vcc
	v_cmp_gt_i32_e32 vcc, 0x218, v184
	s_nop 1
	v_cndmask_b32_e32 v60, v199, v60, vcc
	v_cmp_gt_i32_e32 vcc, 0x219, v184
	s_nop 1
	v_cndmask_b32_e32 v61, v199, v61, vcc
	v_cmp_gt_i32_e32 vcc, 0x21a, v184
	s_nop 1
	v_cndmask_b32_e32 v62, v199, v62, vcc
	v_cmp_gt_i32_e32 vcc, 0x21b, v184
	s_nop 1
	v_cndmask_b32_e32 v63, v199, v63, vcc
